# flat 0->1 barrier invalidates at arrival and the deferred-wait blocks drop their redundant invalidate
# baseline (speedup 1.0000x reference)
.LBB0_66:
	s_cmp_eq_u32 s99, 1
	s_cbranch_scc1 .Lp0_arr_done_a
	s_mov_b32 s99, 1
	s_waitcnt vmcnt(0)
	s_barrier
	s_mov_b64 s[12:13], exec
	v_readlane_b32 s38, v197, 0
	v_readlane_b32 s39, v197, 1
	s_and_b64 s[38:39], s[12:13], s[38:39]
	s_mov_b64 exec, s[38:39]
	s_cbranch_execz .Lp0_arr_m_a
	v_mov_b32_e32 v251, 0
	v_mov_b32_e32 v252, 1
	global_atomic_add v251, v252, s[92:93] offset:160
	buffer_inv sc1

.LBB0_108:
	s_cmp_eq_u32 s99, 1
	s_cbranch_scc1 .Lp0_arr_done_b
	s_mov_b32 s99, 1
	s_waitcnt vmcnt(0)
	s_barrier
	s_mov_b64 s[4:5], exec
	v_readlane_b32 s12, v197, 0
	v_readlane_b32 s13, v197, 1
	s_and_b64 s[12:13], s[4:5], s[12:13]
	s_mov_b64 exec, s[12:13]
	s_cbranch_execz .Lp0_arr_m_b
	v_mov_b32_e32 v251, 0
	v_mov_b32_e32 v252, 1
	global_atomic_add v251, v252, s[92:93] offset:160
	buffer_inv sc1

.Lp0_out:
.Lp0_w_m:
	s_mov_b64 exec, s[0:1]
	s_barrier
	s_branch .LBB0_202
	s_waitcnt vmcnt(0)
	s_barrier
	s_mov_b64 s[0:1], exec
	v_readlane_b32 s2, v197, 0
	v_readlane_b32 s3, v197, 1
	s_and_b64 s[2:3], s[0:1], s[2:3]
	s_mov_b64 exec, s[2:3]
	s_cbranch_execz .LBB0_201
	s_add_i32 s2, 0, 0x24010
	v_mov_b32_e32 v1, s2
	s_waitcnt vmcnt(0) expcnt(0) lgkmcnt(0)
	ds_read_b32 v3, v1
	s_add_i32 s2, 0, 0x24014
	v_mov_b32_e32 v1, s2
	ds_read_b32 v1, v1
	s_waitcnt lgkmcnt(1)
	v_cmp_ne_u32_e32 vcc, 0, v3
	s_cbranch_vccnz .LBB0_165
	v_readlane_b32 s2, v196, 3
	v_readlane_b32 s3, v196, 4
	s_load_dwordx2 s[8:9], s[2:3], 0x4
	s_add_u32 s2, s92, 0x1000
	s_addc_u32 s3, s93, 0
	s_add_u32 s6, s92, 0x1100
	s_addc_u32 s7, s93, 0
	s_waitcnt lgkmcnt(0)
	s_mul_i32 s18, s8, s66
	s_add_u32 s8, s92, 0x1200
	s_mul_i32 s18, s18, s9
	s_addc_u32 s9, s93, 0
	s_add_u32 s10, s92, 0x1300
	s_addc_u32 s11, s93, 0
	s_mov_b32 s19, 1
	v_mov_b32_e32 v17, 0
	s_branch .LBB0_153

.Lbd_out_0:
.Lbd_rest_0:
	s_mov_b64 exec, s[0:1]
